# c7 + phase 6: XCDs 4-7 run the rmsnorm-quant rows before the query GEMM (desynchronised memory bursts)
# speedup vs baseline: 1.1662x; 1.0018x over previous
_Z10fwd_kernel6Params:
	s_load_dwordx2 s[86:87], s[0:1], 0xf0
	s_load_dwordx4 s[76:79], s[0:1], 0xe0
	v_writelane_b32 v254, s0, 0
	s_load_dwordx8 s[68:75], s[0:1], 0xc0
	v_writelane_b32 v255, 0, 46
	s_mov_b32 s81, s2
	v_writelane_b32 v254, s1, 1
	s_waitcnt lgkmcnt(0)
	s_cmp_lt_i32 s86, 0
	s_cbranch_scc1 .LBB0_2
	v_and_b32_e32 v1, 0x3ff, v0
	s_cbranch_execz .LBB0_3
	s_branch .LBB0_14

.LBB0_1570:
	s_cmp_lt_i32 s86, 7
	s_cselect_b64 s[0:1], -1, 0
	s_cmp_gt_i32 s87, 6
	s_cselect_b64 s[2:3], -1, 0
	s_and_b64 s[0:1], s[0:1], s[2:3]
	s_andn2_b64 vcc, exec, s[0:1]
	s_cbranch_vccnz .LBB0_1681
	v_readlane_b32 vcc_lo, v255, 46
	s_cmp_lg_u32 vcc_lo, 0
	s_cbranch_scc1 .Lp6_gemm
	v_readlane_b32 vcc_lo, v254, 44
	s_bitcmp1_b32 vcc_lo, 2
	s_cbranch_scc0 .Lp6_gemm
	s_mov_b32 vcc_lo, 1
	s_nop 3
	v_writelane_b32 v255, vcc_lo, 46
	s_add_u32 s6, s78, 0x18931000
	s_addc_u32 s7, s79, 0
	v_readlane_b32 s0, v254, 0
	v_readlane_b32 s1, v254, 1
	s_nop 3
	s_load_dword s38, s[0:1], 0xf8
	s_branch .LBB0_1594
.Lp6_gemm:
	s_add_u32 s6, s78, 0x18931000
	v_readlane_b32 s0, v254, 0
	s_addc_u32 s7, s79, 0
	v_readlane_b32 s1, v254, 1
	s_add_u32 s39, s78, 0x881000
	s_load_dword s38, s[0:1], 0xf8
	s_addc_u32 s40, s79, 0
	s_add_u32 s4, s0, 0xf8
	s_addc_u32 s5, s1, 0
	s_cmpk_gt_i32 s81, 0x1ff
	s_waitcnt vmcnt(1)
	v_mbcnt_lo_u32_b32 v8, -1, 0
	v_mbcnt_hi_u32_b32 v8, -1, v8
	s_cbranch_scc1 .LBB0_1591
	s_ashr_i32 s41, s81, 31
	s_lshr_b32 s0, s41, 29
	s_add_i32 s8, s81, s0
	s_and_b32 s0, s8, -8
	s_sub_i32 s3, s81, s0
	s_cmp_gt_i32 s3, -1
	s_cbranch_scc0 .LBB0_1574
	s_lshl_b32 s2, s3, 6
	s_ashr_i32 s1, s8, 3
	s_cbranch_execz .LBB0_1575
	s_branch .LBB0_1576

.LBB0_1594:
	v_readlane_b32 vcc_lo, v255, 46
	s_cmp_eq_u32 vcc_lo, 2
	s_cbranch_scc1 .LBB0_1625
	s_lshl_b32 s0, s81, 3
	s_add_i32 s8, s80, s0
	s_cmp_gt_i32 s8, 0x80ff
	v_mbcnt_lo_u32_b32 v0, -1, 0
	v_mbcnt_hi_u32_b32 v0, -1, v0
	s_cbranch_scc1 .Lp6_rows_done
	s_waitcnt lgkmcnt(0)
	s_lshl_b32 s34, s38, 3
	s_add_u32 s35, s78, 0xc219000
	s_addc_u32 s36, s79, 0
	v_lshlrev_b32_e32 v6, 2, v0
	s_add_u32 s37, s78, 0x91b9000
	v_ashrrev_i32_e32 v7, 31, v6
	s_addc_u32 s39, s79, 0
	v_lshl_add_u64 v[4:5], s[78:79], 0, v[6:7]
	s_mov_b64 s[0:1], 0xa1d9000
	s_ashr_i32 s9, s8, 31
	s_lshl_b32 s10, s38, 5
	v_lshl_add_u64 v[4:5], v[4:5], 0, s[0:1]
	s_lshl_b32 s40, s38, 4
	s_lshl_b64 s[0:1], s[8:9], 2
	v_readlane_b32 s12, v254, 18
	s_add_u32 s42, s0, 0x91b9000
	v_readlane_b32 s24, v254, 30
	v_readlane_b32 s25, v254, 31
	s_addc_u32 s43, s1, 0
	s_lshl_b64 s[0:1], s[8:9], 10
	v_cmp_eq_u32_e64 s[2:3], 0, v0
	v_readlane_b32 s13, v254, 19
	v_readlane_b32 s14, v254, 20
	v_readlane_b32 s15, v254, 21
	v_readlane_b32 s16, v254, 22
	v_readlane_b32 s17, v254, 23
	v_readlane_b32 s18, v254, 24
	v_readlane_b32 s19, v254, 25
	v_lshl_add_u64 v[0:1], v[6:7], 2, s[24:25]
	v_lshlrev_b64 v[8:9], 1, v[6:7]
	s_ashr_i32 s11, s10, 31
	v_lshl_add_u64 v[6:7], s[0:1], 0, v[6:7]
	s_lshl_b64 s[0:1], s[8:9], 11
	v_lshl_add_u64 v[2:3], s[6:7], 0, v[8:9]
	s_mul_i32 s41, s38, 24
	s_lshl_b64 s[6:7], s[10:11], 2
	s_lshl_b64 s[12:13], s[10:11], 10
	s_lshl_b64 s[14:15], s[8:9], 3
	s_lshl_b64 s[16:17], s[10:11], 3
	v_lshl_add_u64 v[8:9], s[0:1], 0, v[8:9]
	s_lshl_b64 s[18:19], s[10:11], 11
	v_mov_b32_e32 v68, 0x358637bd
	s_mov_b32 s9, 0x800000
	v_mov_b32_e32 v69, 0
	s_mov_b32 s11, 0x42fe0000
	s_mov_b32 s44, 0xa1d9000
	v_mov_b32_e32 v70, 0xc219000
	v_mov_b32_e32 v71, 0x8000
	v_mov_b32_e32 v72, 0x800000
	v_readlane_b32 s20, v254, 26
	v_readlane_b32 s21, v254, 27
	v_readlane_b32 s22, v254, 28
	v_readlane_b32 s23, v254, 29
	v_readlane_b32 s26, v254, 32
	v_readlane_b32 s27, v254, 33
	s_branch .LBB0_1598

.Lp6_rows_done:
	v_readlane_b32 vcc_lo, v255, 46
	s_cmp_eq_u32 vcc_lo, 1
	s_cbranch_scc0 .LBB0_1625
	s_mov_b32 vcc_lo, 2
	s_nop 3
	v_writelane_b32 v255, vcc_lo, 46
	s_waitcnt vmcnt(0) lgkmcnt(0)
	s_branch .Lp6_gemm
